# swiglu GEMM epilogue: per-row-group store address advanced by one 64-bit add with an SGPR stride instead of re-deriving it (64-bit mad + two adds) per group
# speedup vs baseline: 1.0063x; 1.0030x over previous
; #define GAS __attribute__((address_space(1)))
; DI unsigned pk2(float lo, float hi) { f32x2 v = {lo, hi}; bf16x2_t b = __builtin_convertvector(v, bf16x2_t); return __builtin_bit_cast(unsigned, b); }
; DI float fast_exp2(float x) { return __builtin_amdgcn_exp2f(x); }
; DI float fast_rcp(float x) { return __builtin_amdgcn_rcpf(x); }
;     DI void operator()(const f32x4 (&acc)[2][2][4][2], const Unit& u, int wr, int wc, int fr, int fq) const {
;     ...
;         } else if (mode == 1) {
;             const int col0 = u.pn * (BM / 2) + wc * 32 + 8 * fq;
; #pragma unroll
;             for (int ai = 0; ai < 2; ++ai)
; #pragma unroll
;                 for (int m = 0; m < 4; ++m) { bf16_t* rowp = O + (size_t)(row0 + ai * HALF + m * 16) * ldc + col0; float o[8];
; #pragma unroll
;                     for (int n = 0; n < 2; ++n) { const f32x4 g = acc[ai][0][m][n], up = acc[ai][1][m][n];
; #pragma unroll
;                         for (int j = 0; j < 4; ++j) o[4 * n + j] = g[j] * fast_rcp(1.0f + fast_exp2(-g[j] * LOG2E)) * up[j]; }
;                     u32x4 w; w.x = pk2(o[0], o[1]); w.y = pk2(o[2], o[3]); w.z = pk2(o[4], o[5]); w.w = pk2(o[6], o[7]);
;                     *(GAS u32x4*)rowp = w; }
.LBB0_808:
	s_cbranch_execz .LBB0_810
	v_mul_f32_e32 v131, 0xbfb8aa3b, v122
	v_exp_f32_e32 v132, v131
	v_mul_f32_e32 v131, 0xbfb8aa3b, v123
	v_mul_f32_e32 v136, 0xbfb8aa3b, v124
	v_mul_f32_e32 v137, 0xbfb8aa3b, v125
	v_mul_f32_e32 v138, 0xbfb8aa3b, v126
	v_mul_f32_e32 v139, 0xbfb8aa3b, v127
	v_mul_f32_e32 v140, 0xbfb8aa3b, v128
	v_mul_f32_e32 v141, 0xbfb8aa3b, v129
	v_exp_f32_e32 v133, v131
	v_exp_f32_e32 v136, v136
	v_exp_f32_e32 v137, v137
	v_exp_f32_e32 v138, v138
	v_exp_f32_e32 v139, v139
	v_exp_f32_e32 v140, v140
	v_exp_f32_e32 v141, v141
	v_add_f32_e32 v132, 1.0, v132
	v_add_f32_e32 v133, 1.0, v133
	v_add_f32_e32 v136, 1.0, v136
	v_add_f32_e32 v137, 1.0, v137
	v_add_f32_e32 v138, 1.0, v138
	v_add_f32_e32 v139, 1.0, v139
	v_add_f32_e32 v140, 1.0, v140
	v_add_f32_e32 v141, 1.0, v141
	v_rcp_f32_e32 v132, v132
	v_rcp_f32_e32 v133, v133
	v_rcp_f32_e32 v136, v136
	v_rcp_f32_e32 v137, v137
	v_rcp_f32_e32 v138, v138
	v_rcp_f32_e32 v139, v139
	v_rcp_f32_e32 v140, v140
	v_rcp_f32_e32 v141, v141
	v_lshl_or_b32 v130, s51, 7, v186
	v_ashrrev_i32_e32 v131, 31, v130
	v_mad_i64_i32 v[134:135], s[40:41], v176, s50, 0
	v_pk_mul_f32 v[132:133], v[122:123], v[132:133]
	v_pk_mul_f32 v[136:137], v[124:125], v[136:137]
	v_pk_mul_f32 v[138:139], v[126:127], v[138:139]
	v_pk_mul_f32 v[140:141], v[128:129], v[140:141]
	v_lshl_add_u64 v[134:135], v[134:135], 1, s[30:31]
	v_pk_mul_f32 v[132:133], v[118:119], v[132:133]
	v_pk_mul_f32 v[136:137], v[120:121], v[136:137]
	v_pk_mul_f32 v[138:139], v[114:115], v[138:139]
	v_pk_mul_f32 v[140:141], v[116:117], v[140:141]
	v_lshlrev_b64 v[130:131], 1, v[130:131]
	v_lshl_add_u64 v[142:143], v[134:135], 0, v[130:131]
	v_cvt_pk_bf16_f32 v132, v132, v133
	v_cvt_pk_bf16_f32 v133, v136, v137
	v_cvt_pk_bf16_f32 v134, v138, v139
	v_cvt_pk_bf16_f32 v135, v140, v141
	global_store_dwordx4 v[142:143], v[132:135], off
	s_lshl_b32 s40, s50, 5
	s_mov_b32 s41, 0
	v_mul_f32_e32 v136, 0xbfb8aa3b, v112
	v_mul_f32_e32 v137, 0xbfb8aa3b, v113
	v_mul_f32_e32 v132, 0xbfb8aa3b, v110
	v_mul_f32_e32 v133, 0xbfb8aa3b, v111
	v_mul_f32_e32 v138, 0xbfb8aa3b, v106
	v_mul_f32_e32 v139, 0xbfb8aa3b, v107
	v_mul_f32_e32 v140, 0xbfb8aa3b, v108
	v_mul_f32_e32 v141, 0xbfb8aa3b, v109
	v_exp_f32_e32 v132, v132
	v_exp_f32_e32 v133, v133
	v_exp_f32_e32 v136, v136
	v_exp_f32_e32 v137, v137
	v_exp_f32_e32 v138, v138
	v_exp_f32_e32 v139, v139
	v_exp_f32_e32 v140, v140
	v_exp_f32_e32 v141, v141
	v_add_f32_e32 v132, 1.0, v132
	v_add_f32_e32 v133, 1.0, v133
	v_add_f32_e32 v136, 1.0, v136
	v_add_f32_e32 v137, 1.0, v137
	v_add_f32_e32 v138, 1.0, v138
	v_add_f32_e32 v139, 1.0, v139
	v_add_f32_e32 v140, 1.0, v140
	v_add_f32_e32 v141, 1.0, v141
	v_rcp_f32_e32 v132, v132
	v_rcp_f32_e32 v133, v133
	v_rcp_f32_e32 v136, v136
	v_rcp_f32_e32 v137, v137
	v_rcp_f32_e32 v138, v138
	v_rcp_f32_e32 v139, v139
	v_rcp_f32_e32 v140, v140
	v_rcp_f32_e32 v141, v141
	v_pk_mul_f32 v[132:133], v[110:111], v[132:133]
	v_pk_mul_f32 v[136:137], v[112:113], v[136:137]
	v_pk_mul_f32 v[138:139], v[106:107], v[138:139]
	v_pk_mul_f32 v[140:141], v[108:109], v[140:141]
	v_pk_mul_f32 v[132:133], v[102:103], v[132:133]
	v_pk_mul_f32 v[136:137], v[104:105], v[136:137]
	v_pk_mul_f32 v[138:139], v[98:99], v[138:139]
	v_pk_mul_f32 v[140:141], v[100:101], v[140:141]
	v_lshl_add_u64 v[142:143], v[142:143], 0, s[40:41]
	v_cvt_pk_bf16_f32 v132, v132, v133
	v_cvt_pk_bf16_f32 v133, v136, v137
	v_cvt_pk_bf16_f32 v134, v138, v139
	v_cvt_pk_bf16_f32 v135, v140, v141
	global_store_dwordx4 v[142:143], v[132:135], off
	v_mul_f32_e32 v136, 0xbfb8aa3b, v96
	v_mul_f32_e32 v137, 0xbfb8aa3b, v97
	v_mul_f32_e32 v132, 0xbfb8aa3b, v94
	v_mul_f32_e32 v133, 0xbfb8aa3b, v95
	v_mul_f32_e32 v138, 0xbfb8aa3b, v90
	v_mul_f32_e32 v139, 0xbfb8aa3b, v91
	v_mul_f32_e32 v140, 0xbfb8aa3b, v92
	v_mul_f32_e32 v141, 0xbfb8aa3b, v93
	v_exp_f32_e32 v132, v132
	v_exp_f32_e32 v133, v133
	v_exp_f32_e32 v136, v136
	v_exp_f32_e32 v137, v137
	v_exp_f32_e32 v138, v138
	v_exp_f32_e32 v139, v139
	v_exp_f32_e32 v140, v140
	v_exp_f32_e32 v141, v141
	v_add_f32_e32 v132, 1.0, v132
	v_add_f32_e32 v133, 1.0, v133
	v_add_f32_e32 v136, 1.0, v136
	v_add_f32_e32 v137, 1.0, v137
	v_add_f32_e32 v138, 1.0, v138
	v_add_f32_e32 v139, 1.0, v139
	v_add_f32_e32 v140, 1.0, v140
	v_add_f32_e32 v141, 1.0, v141
	v_rcp_f32_e32 v132, v132
	v_rcp_f32_e32 v133, v133
	v_rcp_f32_e32 v136, v136
	v_rcp_f32_e32 v137, v137
	v_rcp_f32_e32 v138, v138
	v_rcp_f32_e32 v139, v139
	v_rcp_f32_e32 v140, v140
	v_rcp_f32_e32 v141, v141
	v_pk_mul_f32 v[132:133], v[94:95], v[132:133]
	v_pk_mul_f32 v[136:137], v[96:97], v[136:137]
	v_pk_mul_f32 v[138:139], v[90:91], v[138:139]
	v_pk_mul_f32 v[140:141], v[92:93], v[140:141]
	v_pk_mul_f32 v[132:133], v[86:87], v[132:133]
	v_pk_mul_f32 v[136:137], v[88:89], v[136:137]
	v_pk_mul_f32 v[138:139], v[82:83], v[138:139]
	v_pk_mul_f32 v[140:141], v[84:85], v[140:141]
	v_lshl_add_u64 v[142:143], v[142:143], 0, s[40:41]
	v_cvt_pk_bf16_f32 v132, v132, v133
	v_cvt_pk_bf16_f32 v133, v136, v137
	v_cvt_pk_bf16_f32 v134, v138, v139
	v_cvt_pk_bf16_f32 v135, v140, v141
	global_store_dwordx4 v[142:143], v[132:135], off
	v_mul_f32_e32 v136, 0xbfb8aa3b, v80
	v_mul_f32_e32 v137, 0xbfb8aa3b, v81
	v_mul_f32_e32 v132, 0xbfb8aa3b, v78
	v_mul_f32_e32 v133, 0xbfb8aa3b, v79
	v_mul_f32_e32 v138, 0xbfb8aa3b, v74
	v_mul_f32_e32 v139, 0xbfb8aa3b, v75
	v_mul_f32_e32 v140, 0xbfb8aa3b, v76
	v_mul_f32_e32 v141, 0xbfb8aa3b, v77
	v_exp_f32_e32 v132, v132
	v_exp_f32_e32 v133, v133
	v_exp_f32_e32 v136, v136
	v_exp_f32_e32 v137, v137
	v_exp_f32_e32 v138, v138
	v_exp_f32_e32 v139, v139
	v_exp_f32_e32 v140, v140
	v_exp_f32_e32 v141, v141
	v_add_f32_e32 v132, 1.0, v132
	v_add_f32_e32 v133, 1.0, v133
; #define GAS __attribute__((address_space(1)))
; DI unsigned pk2(float lo, float hi) { f32x2 v = {lo, hi}; bf16x2_t b = __builtin_convertvector(v, bf16x2_t); return __builtin_bit_cast(unsigned, b); }
; DI float fast_exp2(float x) { return __builtin_amdgcn_exp2f(x); }
; DI float fast_rcp(float x) { return __builtin_amdgcn_rcpf(x); }
;     DI void operator()(const f32x4 (&acc)[2][2][4][2], const Unit& u, int wr, int wc, int fr, int fq) const {
;     ...
;         } else if (mode == 1) {
;             const int col0 = u.pn * (BM / 2) + wc * 32 + 8 * fq;
; #pragma unroll
;             for (int ai = 0; ai < 2; ++ai)
; #pragma unroll
;                 for (int m = 0; m < 4; ++m) { bf16_t* rowp = O + (size_t)(row0 + ai * HALF + m * 16) * ldc + col0; float o[8];
; #pragma unroll
;                     for (int n = 0; n < 2; ++n) { const f32x4 g = acc[ai][0][m][n], up = acc[ai][1][m][n];
; #pragma unroll
;                         for (int j = 0; j < 4; ++j) o[4 * n + j] = g[j] * fast_rcp(1.0f + fast_exp2(-g[j] * LOG2E)) * up[j]; }
;                     u32x4 w; w.x = pk2(o[0], o[1]); w.y = pk2(o[2], o[3]); w.z = pk2(o[4], o[5]); w.w = pk2(o[6], o[7]);
;                     *(GAS u32x4*)rowp = w; }
	v_add_f32_e32 v136, 1.0, v136
	v_add_f32_e32 v137, 1.0, v137
	v_add_f32_e32 v138, 1.0, v138
	v_add_f32_e32 v139, 1.0, v139
	v_add_f32_e32 v140, 1.0, v140
	v_add_f32_e32 v141, 1.0, v141
	v_rcp_f32_e32 v132, v132
	v_rcp_f32_e32 v133, v133
	v_rcp_f32_e32 v136, v136
	v_rcp_f32_e32 v137, v137
	v_rcp_f32_e32 v138, v138
	v_rcp_f32_e32 v139, v139
	v_rcp_f32_e32 v140, v140
	v_rcp_f32_e32 v141, v141
	v_pk_mul_f32 v[132:133], v[78:79], v[132:133]
	v_pk_mul_f32 v[136:137], v[80:81], v[136:137]
	v_pk_mul_f32 v[138:139], v[74:75], v[138:139]
	v_pk_mul_f32 v[140:141], v[76:77], v[140:141]
	v_pk_mul_f32 v[132:133], v[70:71], v[132:133]
	v_pk_mul_f32 v[136:137], v[72:73], v[136:137]
	v_pk_mul_f32 v[138:139], v[66:67], v[138:139]
	v_pk_mul_f32 v[140:141], v[68:69], v[140:141]
	v_lshl_add_u64 v[142:143], v[142:143], 0, s[40:41]
	v_cvt_pk_bf16_f32 v132, v132, v133
	v_cvt_pk_bf16_f32 v133, v136, v137
	v_cvt_pk_bf16_f32 v134, v138, v139
	v_cvt_pk_bf16_f32 v135, v140, v141
	global_store_dwordx4 v[142:143], v[132:135], off
	v_mul_f32_e32 v136, 0xbfb8aa3b, v64
	v_mul_f32_e32 v137, 0xbfb8aa3b, v65
	v_mul_f32_e32 v132, 0xbfb8aa3b, v62
	v_mul_f32_e32 v133, 0xbfb8aa3b, v63
	v_mul_f32_e32 v138, 0xbfb8aa3b, v58
	v_mul_f32_e32 v139, 0xbfb8aa3b, v59
	v_mul_f32_e32 v140, 0xbfb8aa3b, v60
	v_mul_f32_e32 v141, 0xbfb8aa3b, v61
	v_exp_f32_e32 v132, v132
	v_exp_f32_e32 v133, v133
	v_exp_f32_e32 v136, v136
	v_exp_f32_e32 v137, v137
	v_exp_f32_e32 v138, v138
	v_exp_f32_e32 v139, v139
	v_exp_f32_e32 v140, v140
	v_exp_f32_e32 v141, v141
	v_add_f32_e32 v132, 1.0, v132
	v_add_f32_e32 v133, 1.0, v133
	v_add_f32_e32 v136, 1.0, v136
	v_add_f32_e32 v137, 1.0, v137
	v_add_f32_e32 v138, 1.0, v138
	v_add_f32_e32 v139, 1.0, v139
	v_add_f32_e32 v140, 1.0, v140
	v_add_f32_e32 v141, 1.0, v141
	v_rcp_f32_e32 v132, v132
	v_rcp_f32_e32 v133, v133
	v_rcp_f32_e32 v136, v136
	v_rcp_f32_e32 v137, v137
	v_rcp_f32_e32 v138, v138
	v_rcp_f32_e32 v139, v139
	v_rcp_f32_e32 v140, v140
	v_rcp_f32_e32 v141, v141
	v_pk_mul_f32 v[132:133], v[62:63], v[132:133]
	v_pk_mul_f32 v[136:137], v[64:65], v[136:137]
	v_pk_mul_f32 v[138:139], v[58:59], v[138:139]
	v_pk_mul_f32 v[140:141], v[60:61], v[140:141]
	v_pk_mul_f32 v[132:133], v[54:55], v[132:133]
	v_pk_mul_f32 v[136:137], v[56:57], v[136:137]
	v_pk_mul_f32 v[138:139], v[50:51], v[138:139]
	v_pk_mul_f32 v[140:141], v[52:53], v[140:141]
	s_mul_i32 s40, s50, 0xa0
	v_lshl_add_u64 v[142:143], v[142:143], 0, s[40:41]
	s_lshl_b32 s40, s50, 5
	v_cvt_pk_bf16_f32 v132, v132, v133
	v_cvt_pk_bf16_f32 v133, v136, v137
	v_cvt_pk_bf16_f32 v134, v138, v139
	v_cvt_pk_bf16_f32 v135, v140, v141
	global_store_dwordx4 v[142:143], v[132:135], off
	v_mul_f32_e32 v136, 0xbfb8aa3b, v48
	v_mul_f32_e32 v137, 0xbfb8aa3b, v49
	v_mul_f32_e32 v132, 0xbfb8aa3b, v46
	v_mul_f32_e32 v133, 0xbfb8aa3b, v47
	v_mul_f32_e32 v138, 0xbfb8aa3b, v42
	v_mul_f32_e32 v139, 0xbfb8aa3b, v43
	v_mul_f32_e32 v140, 0xbfb8aa3b, v44
	v_mul_f32_e32 v141, 0xbfb8aa3b, v45
	v_exp_f32_e32 v132, v132
	v_exp_f32_e32 v133, v133
	v_exp_f32_e32 v136, v136
	v_exp_f32_e32 v137, v137
	v_exp_f32_e32 v138, v138
	v_exp_f32_e32 v139, v139
	v_exp_f32_e32 v140, v140
	v_exp_f32_e32 v141, v141
	v_add_f32_e32 v132, 1.0, v132
	v_add_f32_e32 v133, 1.0, v133
	v_add_f32_e32 v136, 1.0, v136
	v_add_f32_e32 v137, 1.0, v137
	v_add_f32_e32 v138, 1.0, v138
	v_add_f32_e32 v139, 1.0, v139
	v_add_f32_e32 v140, 1.0, v140
	v_add_f32_e32 v141, 1.0, v141
	v_rcp_f32_e32 v132, v132
	v_rcp_f32_e32 v133, v133
	v_rcp_f32_e32 v136, v136
	v_rcp_f32_e32 v137, v137
	v_rcp_f32_e32 v138, v138
	v_rcp_f32_e32 v139, v139
	v_rcp_f32_e32 v140, v140
	v_rcp_f32_e32 v141, v141
	v_pk_mul_f32 v[132:133], v[46:47], v[132:133]
	v_pk_mul_f32 v[136:137], v[48:49], v[136:137]
; #define GAS __attribute__((address_space(1)))
; DI unsigned pk2(float lo, float hi) { f32x2 v = {lo, hi}; bf16x2_t b = __builtin_convertvector(v, bf16x2_t); return __builtin_bit_cast(unsigned, b); }
; DI float fast_exp2(float x) { return __builtin_amdgcn_exp2f(x); }
; DI float fast_rcp(float x) { return __builtin_amdgcn_rcpf(x); }
;     DI void operator()(const f32x4 (&acc)[2][2][4][2], const Unit& u, int wr, int wc, int fr, int fq) const {
;     ...
;         } else if (mode == 1) {
;             const int col0 = u.pn * (BM / 2) + wc * 32 + 8 * fq;
; #pragma unroll
;             for (int ai = 0; ai < 2; ++ai)
; #pragma unroll
;                 for (int m = 0; m < 4; ++m) { bf16_t* rowp = O + (size_t)(row0 + ai * HALF + m * 16) * ldc + col0; float o[8];
; #pragma unroll
;                     for (int n = 0; n < 2; ++n) { const f32x4 g = acc[ai][0][m][n], up = acc[ai][1][m][n];
; #pragma unroll
;                         for (int j = 0; j < 4; ++j) o[4 * n + j] = g[j] * fast_rcp(1.0f + fast_exp2(-g[j] * LOG2E)) * up[j]; }
;                     u32x4 w; w.x = pk2(o[0], o[1]); w.y = pk2(o[2], o[3]); w.z = pk2(o[4], o[5]); w.w = pk2(o[6], o[7]);
;                     *(GAS u32x4*)rowp = w; }
	v_pk_mul_f32 v[138:139], v[42:43], v[138:139]
	v_pk_mul_f32 v[140:141], v[44:45], v[140:141]
	v_pk_mul_f32 v[132:133], v[38:39], v[132:133]
	v_pk_mul_f32 v[136:137], v[40:41], v[136:137]
	v_pk_mul_f32 v[138:139], v[34:35], v[138:139]
	v_pk_mul_f32 v[140:141], v[36:37], v[140:141]
	v_lshl_add_u64 v[142:143], v[142:143], 0, s[40:41]
	v_cvt_pk_bf16_f32 v132, v132, v133
	v_cvt_pk_bf16_f32 v133, v136, v137
	v_cvt_pk_bf16_f32 v134, v138, v139
	v_cvt_pk_bf16_f32 v135, v140, v141
	global_store_dwordx4 v[142:143], v[132:135], off
	v_mul_f32_e32 v136, 0xbfb8aa3b, v32
	v_mul_f32_e32 v137, 0xbfb8aa3b, v33
	v_mul_f32_e32 v132, 0xbfb8aa3b, v30
	v_mul_f32_e32 v133, 0xbfb8aa3b, v31
	v_mul_f32_e32 v138, 0xbfb8aa3b, v26
	v_mul_f32_e32 v139, 0xbfb8aa3b, v27
	v_mul_f32_e32 v140, 0xbfb8aa3b, v28
	v_mul_f32_e32 v141, 0xbfb8aa3b, v29
	v_exp_f32_e32 v132, v132
	v_exp_f32_e32 v133, v133
	v_exp_f32_e32 v136, v136
	v_exp_f32_e32 v137, v137
	v_exp_f32_e32 v138, v138
	v_exp_f32_e32 v139, v139
	v_exp_f32_e32 v140, v140
	v_exp_f32_e32 v141, v141
	v_add_f32_e32 v132, 1.0, v132
	v_add_f32_e32 v133, 1.0, v133
	v_add_f32_e32 v136, 1.0, v136
	v_add_f32_e32 v137, 1.0, v137
	v_add_f32_e32 v138, 1.0, v138
	v_add_f32_e32 v139, 1.0, v139
	v_add_f32_e32 v140, 1.0, v140
	v_add_f32_e32 v141, 1.0, v141
	v_rcp_f32_e32 v132, v132
	v_rcp_f32_e32 v133, v133
	v_rcp_f32_e32 v136, v136
	v_rcp_f32_e32 v137, v137
	v_rcp_f32_e32 v138, v138
	v_rcp_f32_e32 v139, v139
	v_rcp_f32_e32 v140, v140
	v_rcp_f32_e32 v141, v141
	v_pk_mul_f32 v[132:133], v[30:31], v[132:133]
	v_pk_mul_f32 v[136:137], v[32:33], v[136:137]
	v_pk_mul_f32 v[138:139], v[26:27], v[138:139]
	v_pk_mul_f32 v[140:141], v[28:29], v[140:141]
	v_pk_mul_f32 v[132:133], v[22:23], v[132:133]
	v_pk_mul_f32 v[136:137], v[24:25], v[136:137]
	v_pk_mul_f32 v[138:139], v[18:19], v[138:139]
	v_pk_mul_f32 v[140:141], v[20:21], v[140:141]
	v_lshl_add_u64 v[142:143], v[142:143], 0, s[40:41]
	v_cvt_pk_bf16_f32 v132, v132, v133
	v_cvt_pk_bf16_f32 v133, v136, v137
	v_cvt_pk_bf16_f32 v134, v138, v139
	v_cvt_pk_bf16_f32 v135, v140, v141
	global_store_dwordx4 v[142:143], v[132:135], off
	v_mul_f32_e32 v136, 0xbfb8aa3b, v16
	v_mul_f32_e32 v137, 0xbfb8aa3b, v17
	v_mul_f32_e32 v132, 0xbfb8aa3b, v14
	v_mul_f32_e32 v133, 0xbfb8aa3b, v15
	v_mul_f32_e32 v138, 0xbfb8aa3b, v10
	v_mul_f32_e32 v139, 0xbfb8aa3b, v11
	v_mul_f32_e32 v140, 0xbfb8aa3b, v12
	v_mul_f32_e32 v141, 0xbfb8aa3b, v13
	v_exp_f32_e32 v132, v132
	v_exp_f32_e32 v133, v133
	v_exp_f32_e32 v136, v136
	v_exp_f32_e32 v137, v137
	v_exp_f32_e32 v138, v138
	v_exp_f32_e32 v139, v139
	v_exp_f32_e32 v140, v140
	v_exp_f32_e32 v141, v141
	v_add_f32_e32 v132, 1.0, v132
	v_add_f32_e32 v133, 1.0, v133
	v_add_f32_e32 v136, 1.0, v136
	v_add_f32_e32 v137, 1.0, v137
	v_add_f32_e32 v138, 1.0, v138
	v_add_f32_e32 v139, 1.0, v139
	v_add_f32_e32 v140, 1.0, v140
	v_add_f32_e32 v141, 1.0, v141
	v_rcp_f32_e32 v132, v132
	v_rcp_f32_e32 v133, v133
	v_rcp_f32_e32 v136, v136
	v_rcp_f32_e32 v137, v137
	v_rcp_f32_e32 v138, v138
	v_rcp_f32_e32 v139, v139
	v_rcp_f32_e32 v140, v140
	v_rcp_f32_e32 v141, v141
	v_pk_mul_f32 v[132:133], v[14:15], v[132:133]
	v_pk_mul_f32 v[136:137], v[16:17], v[136:137]
	v_pk_mul_f32 v[138:139], v[10:11], v[138:139]
	v_pk_mul_f32 v[140:141], v[12:13], v[140:141]
	v_pk_mul_f32 v[132:133], v[6:7], v[132:133]
	v_pk_mul_f32 v[136:137], v[8:9], v[136:137]
	v_pk_mul_f32 v[138:139], v[2:3], v[138:139]
	v_pk_mul_f32 v[140:141], v[4:5], v[140:141]
	v_lshl_add_u64 v[142:143], v[142:143], 0, s[40:41]
	v_cvt_pk_bf16_f32 v130, v132, v133
	v_cvt_pk_bf16_f32 v131, v136, v137
	v_cvt_pk_bf16_f32 v132, v138, v139
	v_cvt_pk_bf16_f32 v133, v140, v141
	global_store_dwordx4 v[142:143], v[130:133], off
